# v25_nonop
# speedup vs baseline: 1.0117x; 1.0117x over previous
; __device__ __forceinline__ float bflo(u32 v) { return __uint_as_float(v << 16); }
; __device__ __forceinline__ float bfhi(u32 v) { return __uint_as_float(v & 0xffff0000u); }
; __device__ __forceinline__ float sigmoidf_(float x) { return 1.f / (1.f + __expf(-x)); }
; __device__ void phase2c(const Params& p) {
;     ...
;   for (int tok = blockIdx.x * 8 + wid; tok < NTOK; tok += gridDim.x * 8) {
;     {
;       const int hh = lane >> 3;
;       float l0 = p.LSE[((size_t)0 * NTOK + tok) * 8 + hh];
;       float l1 = p.LSE[((size_t)1 * NTOK + tok) * 8 + hh];
;       float l2 = p.LSE[((size_t)2 * NTOK + tok) * 8 + hh];
;       float mx = fmaxf(l0, fmaxf(l1, l2));
;       float w0 = __expf(l0 - mx), w1 = __expf(l1 - mx), w2 = __expf(l2 - mx);
;       float inv = 1.f / (w0 + w1 + w2);
;       w0 *= inv; w1 *= inv; w2 *= inv;
; #pragma unroll
;       for (int hf = 0; hf < 2; ++hf) {
;         const int col = 16 * lane + 8 * hf;
;         u32x4 o0 = *(const u32x4*)(p.OG + ((size_t)0 * NTOK + tok) * 1024 + col);
;         u32x4 o1 = *(const u32x4*)(p.OG + ((size_t)1 * NTOK + tok) * 1024 + col);
;         u32x4 o2 = *(const u32x4*)(p.OG + ((size_t)2 * NTOK + tok) * 1024 + col);
;         u32x4 zz = *(const u32x4*)(p.PROJ + (size_t)tok * NP + C_AZ + col);
;         u32x4 res;
; #pragma unroll
;         for (int i = 0; i < 4; ++i) {
;           float za = bflo(zz[i]), zb = bfhi(zz[i]);
;           float va = (w0 * bflo(o0[i]) + w1 * bflo(o1[i]) + w2 * bflo(o2[i])) * za * sigmoidf_(za);
;           float vb = (w0 * bfhi(o0[i]) + w1 * bfhi(o1[i]) + w2 * bfhi(o2[i])) * zb * sigmoidf_(zb);
;           res[i] = pack2(va, vb);
;         }
;         *(u32x4*)(p.YA + (size_t)tok * 1024 + col) = res;
;       }
;     }
.LBB0_513:
	v_ashrrev_i32_e32 v25, 31, v24
	v_lshl_add_u64 v[2:3], v[24:25], 0, s[12:13]
	v_lshlrev_b64 v[4:5], 5, v[2:3]
	v_lshl_add_u64 v[10:11], v[24:25], 0, s[14:15]
	v_lshl_add_u64 v[8:9], v[28:29], 0, v[4:5]
	v_lshlrev_b64 v[4:5], 5, v[10:11]
	v_lshlrev_b64 v[20:21], 11, v[24:25]
	v_lshlrev_b64 v[0:1], 5, v[24:25]
	v_lshl_add_u64 v[12:13], v[28:29], 0, v[4:5]
	v_lshl_add_u64 v[18:19], v[38:39], 0, v[20:21]
	v_lshl_add_u64 v[0:1], v[28:29], 0, v[0:1]
	global_load_dwordx4 v[4:7], v[18:19], off
	global_load_dword v57, v[0:1], off
	global_load_dword v60, v[8:9], off
	global_load_dword v61, v[12:13], off
	v_lshlrev_b64 v[12:13], 15, v[24:25]
	v_lshlrev_b64 v[0:1], 11, v[2:3]
	v_lshlrev_b64 v[2:3], 11, v[10:11]
	v_lshl_add_u64 v[16:17], s[74:75], 0, v[12:13]
	v_lshl_add_u64 v[22:23], v[38:39], 0, v[0:1]
	v_lshl_add_u64 v[46:47], v[38:39], 0, v[2:3]
	v_lshl_add_u64 v[48:49], v[16:17], 0, s[16:17]
	global_load_dwordx4 v[8:11], v[22:23], off
	global_load_dwordx4 v[0:3], v[46:47], off
	v_lshl_add_u64 v[12:13], v[48:49], 0, v[42:43]
	global_load_dwordx4 v[12:15], v[12:13], off
	s_mov_b32 s100, s3
	s_mov_b32 s101, 0
	v_lshlrev_b64 v[228:229], 12, v[24:25]
	v_lshl_add_u64 v[236:237], v[48:49], 0, v[44:45]
	v_lshl_add_u64 v[234:235], v[16:17], 0, v[26:27]
	v_lshl_add_u64 v[230:231], v[30:31], 0, v[228:229]
	v_lshl_add_u64 v[232:233], v[32:33], 0, v[228:229]
	v_lshl_add_u64 v[234:235], v[234:235], 0, s[100:101]
	global_load_dwordx4 v[128:131], v[236:237], off
	global_load_dwordx4 v[132:135], v[22:23], off offset:16
	global_load_dwordx4 v[136:139], v[18:19], off offset:16
	global_load_dwordx4 v[140:143], v[46:47], off offset:16
	global_load_dwordx4 v[144:147], v[230:231], off offset:48
	global_load_dwordx4 v[148:151], v[232:233], off offset:48
	global_load_dwordx4 v[152:155], v[230:231], off
	global_load_dwordx4 v[156:159], v[232:233], off
	global_load_dwordx4 v[160:163], v[234:235], off
	global_load_dwordx4 v[164:167], v[230:231], off offset:32
	global_load_dwordx4 v[168:171], v[230:231], off offset:16
	global_load_dwordx4 v[172:175], v[232:233], off offset:32
	global_load_dwordx4 v[176:179], v[232:233], off offset:16
	global_load_dwordx4 v[180:183], v[34:35], off offset:16
	global_load_dwordx4 v[184:187], v[34:35], off
	global_load_dwordx4 v[192:195], v[234:235], off offset:16
	global_load_dwordx4 v[196:199], v[34:35], off offset:32
	global_load_dwordx4 v[200:203], v[34:35], off offset:48
	global_load_dwordx4 v[204:207], v[234:235], off offset:32
	global_load_dwordx4 v[208:211], v[34:35], off offset:64
	global_load_dwordx4 v[212:215], v[34:35], off offset:80
	global_load_dwordx4 v[216:219], v[234:235], off offset:48
	global_load_dwordx4 v[220:223], v[34:35], off offset:96
	global_load_dwordx4 v[224:227], v[34:35], off offset:112
	s_waitcnt vmcnt(24)
	v_and_b32_e32 v51, 0xffff0000, v4
	v_lshlrev_b32_e32 v52, 16, v4
	v_and_b32_e32 v55, 0xffff0000, v5
	v_max3_f32 v4, v57, v60, v61
	v_lshlrev_b32_e32 v56, 16, v5
	v_sub_f32_e32 v5, v60, v4
	v_lshlrev_b32_e32 v50, 16, v8
	v_lshlrev_b32_e32 v58, 16, v0
	v_and_b32_e32 v59, 0xffff0000, v0
	v_sub_f32_e32 v0, v57, v4
	v_and_b32_e32 v53, 0xffff0000, v8
	v_sub_f32_e32 v4, v61, v4
	v_lshlrev_b32_e32 v60, 16, v12
	v_and_b32_e32 v61, 0xffff0000, v12
	v_mul_f32_e32 v0, 0x3fb8aa3b, v0
	v_mul_f32_e32 v8, 0x3fb8aa3b, v5
	v_mul_f32_e32 v57, 0x3fb8aa3b, v4
	v_mul_f32_e32 v62, 0xbfb8aa3b, v60
	v_mul_f32_e32 v63, 0xbfb8aa3b, v61
	v_exp_f32_e32 v5, v0
	v_exp_f32_e32 v4, v8
	v_exp_f32_e32 v62, v62
	v_exp_f32_e32 v63, v63
	v_exp_f32_e32 v0, v57
	v_add_f32_e32 v8, v5, v4
	v_lshlrev_b32_e32 v12, 16, v13
	v_pk_add_f32 v[62:63], v[62:63], 1.0 op_sel_hi:[1,0]
	v_add_f32_e32 v8, v0, v8
	v_and_b32_e32 v13, 0xffff0000, v13
	v_mul_f32_e32 v64, 0xbfb8aa3b, v12
	v_mul_f32_e32 v65, 0xbfb8aa3b, v13
	v_exp_f32_e32 v64, v64
	v_exp_f32_e32 v65, v65
	v_rcp_f32_e32 v8, v8
	v_pk_add_f32 v[64:65], v[64:65], 1.0 op_sel_hi:[1,0]
	v_pk_mul_f32 v[4:5], v[4:5], v[8:9] op_sel_hi:[1,0]
	s_mov_b64 vcc, s[0:1]
	v_pk_mul_f32 v[52:53], v[4:5], v[52:53] op_sel:[1,0] op_sel_hi:[0,1]
	v_mul_f32_e32 v0, v0, v8
	s_mov_b64 vcc, s[4:5]
	v_pk_fma_f32 v[50:51], v[4:5], v[50:51], v[52:53]
	v_pk_fma_f32 v[50:51], v[0:1], v[58:59], v[50:51] op_sel_hi:[0,1,1]
	v_rcp_f32_e32 v63, v63
	v_rcp_f32_e32 v62, v62
	v_pk_mul_f32 v[50:51], v[50:51], v[60:61]
	v_lshlrev_b32_e32 v54, 16, v9
	v_pk_mul_f32 v[50:51], v[62:63], v[50:51]
	v_and_b32_e32 v57, 0xffff0000, v9
	v_cvt_pk_bf16_f32 v8, v50, v51
	v_lshlrev_b32_e32 v50, 16, v1
	v_and_b32_e32 v51, 0xffff0000, v1
	v_rcp_f32_e32 v53, v65
	v_pk_mul_f32 v[56:57], v[4:5], v[56:57] op_sel:[1,0] op_sel_hi:[0,1]
	s_nop 0
	v_pk_fma_f32 v[54:55], v[4:5], v[54:55], v[56:57]
	v_rcp_f32_e32 v52, v64
	v_pk_fma_f32 v[50:51], v[0:1], v[50:51], v[54:55] op_sel_hi:[0,1,1]
	v_pk_mul_f32 v[12:13], v[50:51], v[12:13]
	v_lshlrev_b32_e32 v54, 16, v6
	v_pk_mul_f32 v[12:13], v[52:53], v[12:13]
	v_and_b32_e32 v53, 0xffff0000, v6
	v_cvt_pk_bf16_f32 v9, v12, v13
	v_lshlrev_b32_e32 v12, 16, v14
	v_and_b32_e32 v13, 0xffff0000, v14
	v_mul_f32_e32 v1, 0xbfb8aa3b, v12
	v_exp_f32_e32 v50, v1
	v_mul_f32_e32 v1, 0xbfb8aa3b, v13
	v_exp_f32_e32 v51, v1
	v_lshlrev_b32_e32 v56, 16, v2
	v_and_b32_e32 v57, 0xffff0000, v2
	v_lshlrev_b32_e32 v52, 16, v10
	v_pk_add_f32 v[50:51], v[50:51], 1.0 op_sel_hi:[1,0]
	v_and_b32_e32 v55, 0xffff0000, v10
	v_pk_mul_f32 v[54:55], v[4:5], v[54:55] op_sel:[1,0] op_sel_hi:[0,1]
	v_pk_fma_f32 v[52:53], v[4:5], v[52:53], v[54:55]
	v_rcp_f32_e32 v51, v51
	v_pk_fma_f32 v[52:53], v[0:1], v[56:57], v[52:53] op_sel_hi:[0,1,1]
	v_rcp_f32_e32 v50, v50
	v_pk_mul_f32 v[12:13], v[52:53], v[12:13]
	v_lshlrev_b32_e32 v14, 16, v11
	v_pk_mul_f32 v[12:13], v[50:51], v[12:13]
	v_lshlrev_b32_e32 v50, 16, v7
	v_cvt_pk_bf16_f32 v10, v12, v13
	v_lshlrev_b32_e32 v12, 16, v15
	v_and_b32_e32 v13, 0xffff0000, v15
	v_mul_f32_e32 v1, 0xbfb8aa3b, v12
	v_exp_f32_e32 v6, v1
	v_mul_f32_e32 v1, 0xbfb8aa3b, v13
	v_and_b32_e32 v15, 0xffff0000, v7
	v_exp_f32_e32 v7, v1
	v_and_b32_e32 v51, 0xffff0000, v11
	v_pk_mul_f32 v[50:51], v[4:5], v[50:51] op_sel:[1,0] op_sel_hi:[0,1]
	v_pk_fma_f32 v[14:15], v[4:5], v[14:15], v[50:51]
	v_pk_add_f32 v[6:7], v[6:7], 1.0 op_sel_hi:[1,0]
	v_lshlrev_b32_e32 v2, 16, v3
	v_and_b32_e32 v3, 0xffff0000, v3
	v_pk_fma_f32 v[2:3], v[0:1], v[2:3], v[14:15] op_sel_hi:[0,1,1]
	v_pk_mul_f32 v[2:3], v[2:3], v[12:13]
	v_rcp_f32_e32 v7, v7
	v_lshlrev_b64 v[56:57], 12, v[24:25]
	v_rcp_f32_e32 v6, v6
	s_nop 0
	v_pk_mul_f32 v[2:3], v[6:7], v[2:3]
	v_lshl_add_u64 v[6:7], v[48:49], 0, v[44:45]
	v_cvt_pk_bf16_f32 v11, v2, v3
	v_lshl_add_u64 v[2:3], v[40:41], 0, v[20:21]
	global_store_dwordx4 v[2:3], v[8:11], off
	s_waitcnt vmcnt(21)
; __device__ __forceinline__ float bflo(u32 v) { return __uint_as_float(v << 16); }
; __device__ __forceinline__ float bfhi(u32 v) { return __uint_as_float(v & 0xffff0000u); }
; __device__ __forceinline__ float sigmoidf_(float x) { return 1.f / (1.f + __expf(-x)); }
; __device__ void phase2c(const Params& p) {
;     ...
; #pragma unroll
;       for (int hf = 0; hf < 2; ++hf) {
;         const int col = 16 * lane + 8 * hf;
;         u32x4 o0 = *(const u32x4*)(p.OG + ((size_t)0 * NTOK + tok) * 1024 + col);
;         u32x4 o1 = *(const u32x4*)(p.OG + ((size_t)1 * NTOK + tok) * 1024 + col);
;         u32x4 o2 = *(const u32x4*)(p.OG + ((size_t)2 * NTOK + tok) * 1024 + col);
;         u32x4 zz = *(const u32x4*)(p.PROJ + (size_t)tok * NP + C_AZ + col);
;         u32x4 res;
; #pragma unroll
;         for (int i = 0; i < 4; ++i) {
;           float za = bflo(zz[i]), zb = bfhi(zz[i]);
;           float va = (w0 * bflo(o0[i]) + w1 * bflo(o1[i]) + w2 * bflo(o2[i])) * za * sigmoidf_(za);
;           float vb = (w0 * bfhi(o0[i]) + w1 * bfhi(o1[i]) + w2 * bfhi(o2[i])) * zb * sigmoidf_(zb);
;           res[i] = pack2(va, vb);
;         }
;         *(u32x4*)(p.YA + (size_t)tok * 1024 + col) = res;
;       }
;     }
;     {
;       const int col0 = 32 * lane;
;       f32x4 v[8];
;       float ss = 0.f;
; #pragma unroll
;       for (int i = 0; i < 4; ++i) {
;         u32x4 a = *(const u32x4*)(p.OF + (size_t)tok * 2048 + col0 + 8 * i);
;         u32x4 b = *(const u32x4*)(p.OB + (size_t)tok * 2048 + col0 + 8 * i);
;         v[2 * i] = f32x4{bflo(a[0]) + bflo(b[0]), bfhi(a[0]) + bfhi(b[0]), bflo(a[1]) + bflo(b[1]), bfhi(a[1]) + bfhi(b[1])};
;         v[2 * i + 1] = f32x4{bflo(a[2]) + bflo(b[2]), bfhi(a[2]) + bfhi(b[2]), bflo(a[3]) + bflo(b[3]), bfhi(a[3]) + bfhi(b[3])};
	v_add_u32_e32 v24, s2, v24
	v_lshlrev_b32_e32 v14, 16, v128
	v_and_b32_e32 v15, 0xffff0000, v128
	v_mul_f32_e32 v1, 0xbfb8aa3b, v14
	v_exp_f32_e32 v22, v1
	v_mul_f32_e32 v1, 0xbfb8aa3b, v15
	v_exp_f32_e32 v23, v1
	v_lshlrev_b32_e32 v50, 16, v132
	v_and_b32_e32 v53, 0xffff0000, v132
	v_lshlrev_b32_e32 v52, 16, v136
	v_pk_add_f32 v[22:23], v[22:23], 1.0 op_sel_hi:[1,0]
	v_and_b32_e32 v51, 0xffff0000, v136
	v_pk_mul_f32 v[52:53], v[4:5], v[52:53] op_sel:[1,0] op_sel_hi:[0,1]
	v_pk_fma_f32 v[50:51], v[4:5], v[50:51], v[52:53]
	v_lshlrev_b32_e32 v52, 16, v140
	v_and_b32_e32 v53, 0xffff0000, v140
	v_pk_fma_f32 v[50:51], v[0:1], v[52:53], v[50:51] op_sel_hi:[0,1,1]
	v_rcp_f32_e32 v23, v23
	v_pk_mul_f32 v[14:15], v[50:51], v[14:15]
	v_rcp_f32_e32 v22, v22
	s_nop 0
	v_pk_mul_f32 v[14:15], v[14:15], v[22:23]
	v_lshlrev_b32_e32 v22, 16, v133
	v_cvt_pk_bf16_f32 v6, v14, v15
	v_lshlrev_b32_e32 v14, 16, v129
	v_and_b32_e32 v15, 0xffff0000, v129
	v_mul_f32_e32 v1, 0xbfb8aa3b, v14
	v_exp_f32_e32 v10, v1
	v_mul_f32_e32 v1, 0xbfb8aa3b, v15
	v_and_b32_e32 v23, 0xffff0000, v137
	v_lshlrev_b32_e32 v18, 16, v137
	v_and_b32_e32 v19, 0xffff0000, v133
	v_exp_f32_e32 v11, v1
	v_pk_mul_f32 v[18:19], v[4:5], v[18:19] op_sel:[1,0] op_sel_hi:[0,1]
	v_pk_fma_f32 v[18:19], v[4:5], v[22:23], v[18:19]
	v_lshlrev_b32_e32 v22, 16, v141
	v_pk_add_f32 v[10:11], v[10:11], 1.0 op_sel_hi:[1,0]
	v_and_b32_e32 v23, 0xffff0000, v141
	v_pk_fma_f32 v[18:19], v[0:1], v[22:23], v[18:19] op_sel_hi:[0,1,1]
	v_pk_mul_f32 v[14:15], v[18:19], v[14:15]
	v_and_b32_e32 v23, 0xffff0000, v134
	v_rcp_f32_e32 v11, v11
	v_rcp_f32_e32 v10, v10
	s_nop 0
	v_pk_mul_f32 v[10:11], v[14:15], v[10:11]
	v_lshlrev_b32_e32 v22, 16, v138
	v_cvt_pk_bf16_f32 v7, v10, v11
	v_lshlrev_b32_e32 v10, 16, v130
	v_and_b32_e32 v11, 0xffff0000, v130
	v_mul_f32_e32 v1, 0xbfb8aa3b, v10
	v_exp_f32_e32 v14, v1
	v_mul_f32_e32 v1, 0xbfb8aa3b, v11
	v_exp_f32_e32 v15, v1
	v_lshlrev_b32_e32 v18, 16, v134
	v_and_b32_e32 v19, 0xffff0000, v138
	v_pk_mul_f32 v[22:23], v[4:5], v[22:23] op_sel:[1,0] op_sel_hi:[0,1]
	v_pk_add_f32 v[14:15], v[14:15], 1.0 op_sel_hi:[1,0]
	v_pk_fma_f32 v[18:19], v[4:5], v[18:19], v[22:23]
	v_lshlrev_b32_e32 v22, 16, v142
	v_and_b32_e32 v23, 0xffff0000, v142
	v_pk_fma_f32 v[18:19], v[0:1], v[22:23], v[18:19] op_sel_hi:[0,1,1]
	v_pk_mul_f32 v[10:11], v[18:19], v[10:11]
	v_rcp_f32_e32 v15, v15
	v_rcp_f32_e32 v14, v14
	s_nop 0
	v_pk_mul_f32 v[10:11], v[10:11], v[14:15]
	v_lshlrev_b32_e32 v14, 16, v135
	v_cvt_pk_bf16_f32 v8, v10, v11
	v_lshlrev_b32_e32 v10, 16, v131
	v_and_b32_e32 v11, 0xffff0000, v131
	v_mul_f32_e32 v1, 0xbfb8aa3b, v10
	v_exp_f32_e32 v12, v1
	v_mul_f32_e32 v1, 0xbfb8aa3b, v11
	v_and_b32_e32 v19, 0xffff0000, v135
	v_exp_f32_e32 v13, v1
	v_lshlrev_b32_e32 v18, 16, v139
	v_and_b32_e32 v15, 0xffff0000, v139
	v_pk_mul_f32 v[18:19], v[4:5], v[18:19] op_sel:[1,0] op_sel_hi:[0,1]
	v_pk_add_f32 v[12:13], v[12:13], 1.0 op_sel_hi:[1,0]
	v_pk_fma_f32 v[4:5], v[4:5], v[14:15], v[18:19]
	v_lshlrev_b32_e32 v14, 16, v143
	v_and_b32_e32 v15, 0xffff0000, v143
	v_pk_fma_f32 v[0:1], v[0:1], v[14:15], v[4:5] op_sel_hi:[0,1,1]
	v_pk_mul_f32 v[0:1], v[0:1], v[10:11]
	v_rcp_f32_e32 v5, v13
	v_lshl_add_u64 v[18:19], v[32:33], 0, v[56:57]
	v_rcp_f32_e32 v4, v12
	s_nop 0
	v_pk_mul_f32 v[0:1], v[0:1], v[4:5]
	v_lshl_add_u64 v[10:11], v[16:17], 0, v[26:27]
	v_cvt_pk_bf16_f32 v9, v0, v1
	global_store_dwordx4 v[2:3], v[6:9], off offset:16
	s_waitcnt vmcnt(11)
	v_add_co_u32_e32 v54, vcc, s3, v10
	v_lshl_add_u64 v[8:9], v[30:31], 0, v[56:57]
	s_nop 0
	v_addc_co_u32_e32 v55, vcc, 0, v11, vcc
	v_lshlrev_b32_e32 v49, 16, v148
	v_lshlrev_b32_e32 v58, 16, v155
	v_and_b32_e32 v59, 0xffff0000, v155
	v_lshlrev_b32_e32 v60, 16, v159
	v_and_b32_e32 v61, 0xffff0000, v159
	v_pk_add_f32 v[58:59], v[58:59], v[60:61]
	v_lshlrev_b32_e32 v60, 16, v162
	v_and_b32_e32 v61, 0xffff0000, v162
	v_mul_f32_e32 v25, 0xbfb8aa3b, v60
	v_exp_f32_e32 v62, v25
	v_mul_f32_e32 v25, 0xbfb8aa3b, v61
	v_exp_f32_e32 v63, v25
	v_lshlrev_b32_e32 v72, 16, v154
	v_and_b32_e32 v73, 0xffff0000, v154
	v_lshlrev_b32_e32 v68, 16, v158
	v_pk_add_f32 v[76:77], v[62:63], 1.0 op_sel_hi:[1,0]
	v_and_b32_e32 v69, 0xffff0000, v158
	v_pk_add_f32 v[62:63], v[72:73], v[68:69]
	v_and_b32_e32 v79, 0xffff0000, v153
	v_lshlrev_b32_e32 v80, 16, v157
	v_rcp_f32_e32 v69, v77
	v_lshlrev_b32_e32 v78, 16, v153
	v_lshlrev_b32_e32 v72, 16, v161
	v_rcp_f32_e32 v68, v76
	v_and_b32_e32 v73, 0xffff0000, v161
	v_mul_f32_e32 v25, 0xbfb8aa3b, v72
	v_exp_f32_e32 v76, v25
	v_mul_f32_e32 v25, 0xbfb8aa3b, v73
	v_exp_f32_e32 v77, v25
	v_and_b32_e32 v81, 0xffff0000, v157
	v_lshlrev_b32_e32 v47, 16, v144
	v_lshlrev_b32_e32 v46, 16, v146
	v_pk_add_f32 v[90:91], v[76:77], 1.0 op_sel_hi:[1,0]
	v_pk_add_f32 v[76:77], v[78:79], v[80:81]
	v_lshlrev_b32_e32 v48, 16, v150
	v_pk_add_f32 v[50:51], v[46:47], v[48:49]
	v_and_b32_e32 v47, 0xffff0000, v144
	v_rcp_f32_e32 v79, v91
	v_and_b32_e32 v46, 0xffff0000, v146
	v_lshlrev_b32_e32 v80, 16, v160
	v_rcp_f32_e32 v78, v90
	v_and_b32_e32 v81, 0xffff0000, v160
	v_mul_f32_e32 v25, 0xbfb8aa3b, v80
	v_exp_f32_e32 v90, v25
	v_mul_f32_e32 v25, 0xbfb8aa3b, v81
	v_and_b32_e32 v49, 0xffff0000, v148
	v_and_b32_e32 v48, 0xffff0000, v150
	v_exp_f32_e32 v91, v25
	v_pk_add_f32 v[52:53], v[46:47], v[48:49]
	v_lshlrev_b32_e32 v47, 16, v145
	v_lshlrev_b32_e32 v46, 16, v147
	v_lshlrev_b32_e32 v49, 16, v149
	v_lshlrev_b32_e32 v48, 16, v151
	v_and_b32_e32 v1, 0xffff0000, v145
	v_and_b32_e32 v0, 0xffff0000, v147
	v_and_b32_e32 v3, 0xffff0000, v149
	v_and_b32_e32 v2, 0xffff0000, v151
	v_pk_add_f32 v[46:47], v[46:47], v[48:49]
	v_pk_add_f32 v[48:49], v[0:1], v[2:3]
	v_pk_mul_f32 v[0:1], v[52:53], v[52:53]
; __device__ __forceinline__ float bflo(u32 v) { return __uint_as_float(v << 16); }
; __device__ __forceinline__ float bfhi(u32 v) { return __uint_as_float(v & 0xffff0000u); }
; __device__ __forceinline__ float sigmoidf_(float x) { return 1.f / (1.f + __expf(-x)); }
; __device__ void phase2c(const Params& p) {
;     ...
; #pragma unroll
;       for (int i = 0; i < 8; ++i) ss += v[i][0] * v[i][0] + v[i][1] * v[i][1] + v[i][2] * v[i][2] + v[i][3] * v[i][3];
;       ss += __shfl_xor(ss, 1);
;       ss += __shfl_xor(ss, 2);
;       ss += __shfl_xor(ss, 4);
;       ss += __shfl_xor(ss, 8);
;       const float r = rsqrtf(ss * (1.f / 512.f) + EPS);
; #pragma unroll
;       for (int i = 0; i < 4; ++i) {
;         u32x4 zz = *(const u32x4*)(p.PROJ + (size_t)tok * NP + C_GZ + col0 + 8 * i);
;         f32x4 g0 = *(const f32x4*)(p.gla_g + ((col0 + 8 * i) & 511));
;         f32x4 g1 = *(const f32x4*)(p.gla_g + ((col0 + 8 * i + 4) & 511));
;         u32x4 res;
; #pragma unroll
;         for (int q = 0; q < 4; ++q) {
;           float za = bflo(zz[q]), zb = bfhi(zz[q]);
;           float ga = (q < 2) ? g0[2 * q] : g1[2 * q - 4];
;           float gb = (q < 2) ? g0[2 * q + 1] : g1[2 * q - 3];
;           float xa = (q < 2) ? v[2 * i][2 * q] : v[2 * i + 1][2 * q - 4];
;           float xb = (q < 2) ? v[2 * i][2 * q + 1] : v[2 * i + 1][2 * q - 3];
;           res[q] = pack2(xa * r * ga * za * sigmoidf_(za), xb * r * gb * zb * sigmoidf_(zb));
;         }
;         *(u32x4*)(p.YB + (size_t)tok * 2048 + col0 + 8 * i) = res;
	v_pk_add_f32 v[90:91], v[90:91], 1.0 op_sel_hi:[1,0]
	v_pk_fma_f32 v[0:1], v[50:51], v[50:51], v[0:1]
	v_pk_fma_f32 v[0:1], v[46:47], v[46:47], v[0:1]
	v_pk_fma_f32 v[64:65], v[48:49], v[48:49], v[0:1]
	v_lshlrev_b32_e32 v92, 16, v152
	v_and_b32_e32 v93, 0xffff0000, v152
	v_lshlrev_b32_e32 v66, 16, v156
	v_and_b32_e32 v67, 0xffff0000, v156
	v_pk_add_f32 v[88:89], v[92:93], v[66:67]
	v_rcp_f32_e32 v91, v91
	v_lshlrev_b32_e32 v94, 16, v163
	v_and_b32_e32 v95, 0xffff0000, v163
	v_mul_f32_e32 v66, 0xbfb8aa3b, v94
	v_mul_f32_e32 v67, 0xbfb8aa3b, v95
	v_exp_f32_e32 v66, v66
	v_exp_f32_e32 v67, v67
	s_nop 0
	v_pk_add_f32 v[98:99], v[66:67], 1.0 op_sel_hi:[1,0]
	v_lshlrev_b32_e32 v66, 16, v171
	v_and_b32_e32 v67, 0xffff0000, v171
	v_lshlrev_b32_e32 v100, 16, v179
	v_and_b32_e32 v101, 0xffff0000, v179
	v_pk_add_f32 v[66:67], v[66:67], v[100:101]
	v_lshlrev_b32_e32 v100, 16, v170
	v_and_b32_e32 v101, 0xffff0000, v170
	v_lshlrev_b32_e32 v22, 16, v178
	v_and_b32_e32 v23, 0xffff0000, v178
	v_pk_add_f32 v[22:23], v[100:101], v[22:23]
	v_lshlrev_b32_e32 v18, 16, v169
	v_and_b32_e32 v19, 0xffff0000, v169
	v_lshlrev_b32_e32 v100, 16, v177
	v_and_b32_e32 v101, 0xffff0000, v177
	v_pk_add_f32 v[100:101], v[18:19], v[100:101]
	v_lshlrev_b32_e32 v18, 16, v168
	v_and_b32_e32 v19, 0xffff0000, v168
	v_lshlrev_b32_e32 v20, 16, v176
	v_and_b32_e32 v21, 0xffff0000, v176
	v_pk_add_f32 v[20:21], v[18:19], v[20:21]
	v_mov_b32_e32 v104, v23
	v_mov_b32_e32 v105, v21
	v_mov_b32_e32 v102, v22
	v_mov_b32_e32 v103, v20
	v_pk_mul_f32 v[104:105], v[104:105], v[104:105]
	v_mov_b32_e32 v16, v66
	v_mov_b32_e32 v17, v100
	v_pk_fma_f32 v[102:103], v[102:103], v[102:103], v[104:105]
	v_mov_b32_e32 v18, v67
	v_mov_b32_e32 v19, v101
	v_pk_fma_f32 v[16:17], v[16:17], v[16:17], v[102:103]
	v_pk_mul_f32 v[74:75], v[62:63], v[62:63]
	v_pk_fma_f32 v[102:103], v[18:19], v[18:19], v[16:17]
	v_lshlrev_b32_e32 v16, 16, v167
	v_and_b32_e32 v17, 0xffff0000, v167
	v_lshlrev_b32_e32 v18, 16, v175
	v_and_b32_e32 v19, 0xffff0000, v175
	v_pk_add_f32 v[16:17], v[16:17], v[18:19]
	v_lshlrev_b32_e32 v18, 16, v166
	v_and_b32_e32 v19, 0xffff0000, v166
	v_lshlrev_b32_e32 v14, 16, v174
	v_and_b32_e32 v15, 0xffff0000, v174
	v_pk_add_f32 v[14:15], v[18:19], v[14:15]
	v_lshlrev_b32_e32 v10, 16, v165
	v_and_b32_e32 v11, 0xffff0000, v165
	v_lshlrev_b32_e32 v18, 16, v173
	v_and_b32_e32 v19, 0xffff0000, v173
	v_pk_add_f32 v[18:19], v[10:11], v[18:19]
	v_lshlrev_b32_e32 v10, 16, v164
	v_and_b32_e32 v11, 0xffff0000, v164
	v_lshlrev_b32_e32 v12, 16, v172
	v_and_b32_e32 v13, 0xffff0000, v172
	v_pk_add_f32 v[12:13], v[10:11], v[12:13]
	v_mov_b32_e32 v106, v15
	v_mov_b32_e32 v107, v13
	v_mov_b32_e32 v104, v14
	v_mov_b32_e32 v105, v12
	v_pk_mul_f32 v[106:107], v[106:107], v[106:107]
	v_mov_b32_e32 v8, v16
	v_mov_b32_e32 v9, v18
	v_pk_fma_f32 v[104:105], v[104:105], v[104:105], v[106:107]
	v_pk_mul_f32 v[92:93], v[88:89], v[88:89]
	v_mov_b32_e32 v10, v17
	v_mov_b32_e32 v11, v19
	v_pk_fma_f32 v[8:9], v[8:9], v[8:9], v[104:105]
	v_pk_mul_f32 v[70:71], v[58:59], v[58:59]
	v_pk_mul_f32 v[96:97], v[76:77], v[76:77]
	v_pk_fma_f32 v[8:9], v[10:11], v[10:11], v[8:9]
	v_add_f32_e32 v10, v74, v75
	v_add_f32_e32 v11, v92, v93
	v_add_f32_e32 v10, v70, v10
	v_add_f32_e32 v11, v96, v11
	v_add_f32_e32 v10, v71, v10
	v_add_f32_e32 v11, v97, v11
	v_add_f32_e32 v10, v11, v10
	v_add_f32_e32 v10, v10, v103
	v_add_f32_e32 v10, v102, v10
	v_add_f32_e32 v9, v10, v9
	v_add_f32_e32 v8, v8, v9
	v_add_f32_e32 v8, v8, v65
	v_add_f32_e32 v8, v64, v8
	ds_bpermute_b32 v9, v82, v8
	v_rcp_f32_e32 v90, v90
	s_waitcnt lgkmcnt(0)
	v_add_f32_e32 v8, v8, v9
	ds_bpermute_b32 v9, v83, v8
	s_waitcnt lgkmcnt(0)
	v_add_f32_e32 v8, v8, v9
	ds_bpermute_b32 v9, v84, v8
	s_waitcnt lgkmcnt(0)
	v_add_f32_e32 v8, v8, v9
	ds_bpermute_b32 v9, v85, v8
	v_rcp_f32_e32 v65, v99
	s_waitcnt lgkmcnt(0)
	v_add_f32_e32 v8, v8, v9
	v_fmamk_f32 v8, v8, 0x3b000000, v86
	v_mul_f32_e32 v9, 0x4b800000, v8
	v_cmp_gt_f32_e64 s[0:1], s11, v8
	s_nop 1
	v_cndmask_b32_e64 v8, v8, v9, s[0:1]
	v_rsq_f32_e32 v11, v8
	v_rcp_f32_e32 v64, v98
	v_lshl_add_u64 v[8:9], v[36:37], 0, v[56:57]
	v_mul_f32_e32 v10, 0x45800000, v11
	v_cndmask_b32_e64 v10, v11, v10, s[0:1]
	v_pk_mul_f32 v[56:57], v[88:89], v[10:11] op_sel_hi:[1,0]
	v_pk_mul_f32 v[4:5], v[184:185], v[56:57]
	v_pk_mul_f32 v[56:57], v[76:77], v[10:11] op_sel_hi:[1,0]
	v_pk_mul_f32 v[4:5], v[4:5], v[80:81]
	v_pk_mul_f32 v[6:7], v[186:187], v[56:57]
	v_pk_mul_f32 v[4:5], v[90:91], v[4:5]
	v_pk_mul_f32 v[6:7], v[6:7], v[72:73]
	v_cvt_pk_bf16_f32 v4, v4, v5
	v_pk_mul_f32 v[6:7], v[78:79], v[6:7]
	v_cvt_pk_bf16_f32 v5, v6, v7
	v_pk_mul_f32 v[6:7], v[62:63], v[10:11] op_sel_hi:[1,0]
	v_pk_mul_f32 v[0:1], v[180:181], v[6:7]
	v_pk_mul_f32 v[0:1], v[0:1], v[60:61]
	v_pk_mul_f32 v[0:1], v[68:69], v[0:1]
	v_cvt_pk_bf16_f32 v6, v0, v1
	v_pk_mul_f32 v[0:1], v[58:59], v[10:11] op_sel_hi:[1,0]
	v_pk_mul_f32 v[0:1], v[182:183], v[0:1]
	v_pk_mul_f32 v[0:1], v[0:1], v[94:95]
	v_pk_mul_f32 v[0:1], v[64:65], v[0:1]
	v_cvt_pk_bf16_f32 v7, v0, v1
	global_store_dwordx4 v[8:9], v[4:7], off
	s_waitcnt vmcnt(9)
; __device__ __forceinline__ float bflo(u32 v) { return __uint_as_float(v << 16); }
; __device__ __forceinline__ float bfhi(u32 v) { return __uint_as_float(v & 0xffff0000u); }
; __device__ __forceinline__ float sigmoidf_(float x) { return 1.f / (1.f + __expf(-x)); }
; __device__ void phase2c(const Params& p) {
;     ...
;   for (int tok = blockIdx.x * 8 + wid; tok < NTOK; tok += gridDim.x * 8) {
;     ...
;       for (int i = 0; i < 4; ++i) {
;         u32x4 zz = *(const u32x4*)(p.PROJ + (size_t)tok * NP + C_GZ + col0 + 8 * i);
;         f32x4 g0 = *(const f32x4*)(p.gla_g + ((col0 + 8 * i) & 511));
;         f32x4 g1 = *(const f32x4*)(p.gla_g + ((col0 + 8 * i + 4) & 511));
;         u32x4 res;
; #pragma unroll
;         for (int q = 0; q < 4; ++q) {
;           float za = bflo(zz[q]), zb = bfhi(zz[q]);
;           float ga = (q < 2) ? g0[2 * q] : g1[2 * q - 4];
;           float gb = (q < 2) ? g0[2 * q + 1] : g1[2 * q - 3];
;           float xa = (q < 2) ? v[2 * i][2 * q] : v[2 * i + 1][2 * q - 4];
;           float xb = (q < 2) ? v[2 * i][2 * q + 1] : v[2 * i + 1][2 * q - 3];
;           res[q] = pack2(xa * r * ga * za * sigmoidf_(za), xb * r * gb * zb * sigmoidf_(zb));
;         }
;         *(u32x4*)(p.YB + (size_t)tok * 2048 + col0 + 8 * i) = res;
	v_lshlrev_b32_e32 v60, 16, v192
	v_and_b32_e32 v61, 0xffff0000, v192
	v_mul_f32_e32 v0, 0xbfb8aa3b, v60
	v_exp_f32_e32 v62, v0
	v_mul_f32_e32 v0, 0xbfb8aa3b, v61
	v_exp_f32_e32 v63, v0
	s_nop 0
	v_pk_add_f32 v[62:63], v[62:63], 1.0 op_sel_hi:[1,0]
	v_pk_mul_f32 v[20:21], v[20:21], v[10:11] op_sel_hi:[1,0]
	v_pk_mul_f32 v[4:5], v[196:197], v[20:21]
	v_rcp_f32_e32 v21, v63
	v_pk_mul_f32 v[4:5], v[4:5], v[60:61]
	v_lshlrev_b32_e32 v60, 16, v193
	v_and_b32_e32 v61, 0xffff0000, v193
	v_mul_f32_e32 v1, 0xbfb8aa3b, v60
	v_exp_f32_e32 v64, v1
	v_mul_f32_e32 v1, 0xbfb8aa3b, v61
	v_exp_f32_e32 v65, v1
	v_rcp_f32_e32 v20, v62
	s_nop 0
	v_pk_mul_f32 v[0:1], v[20:21], v[4:5]
	v_pk_add_f32 v[4:5], v[64:65], 1.0 op_sel_hi:[1,0]
	v_cvt_pk_bf16_f32 v0, v0, v1
	v_pk_mul_f32 v[20:21], v[100:101], v[10:11] op_sel_hi:[1,0]
	v_pk_mul_f32 v[6:7], v[198:199], v[20:21]
	v_rcp_f32_e32 v5, v5
	v_pk_mul_f32 v[6:7], v[6:7], v[60:61]
	v_lshlrev_b32_e32 v20, 16, v194
	v_and_b32_e32 v21, 0xffff0000, v194
	v_mul_f32_e32 v2, 0xbfb8aa3b, v20
	v_exp_f32_e32 v60, v2
	v_mul_f32_e32 v2, 0xbfb8aa3b, v21
	v_exp_f32_e32 v61, v2
	v_rcp_f32_e32 v4, v4
	s_nop 0
	v_pk_mul_f32 v[4:5], v[4:5], v[6:7]
	v_cvt_pk_bf16_f32 v1, v4, v5
	v_pk_add_f32 v[4:5], v[60:61], 1.0 op_sel_hi:[1,0]
	v_pk_mul_f32 v[6:7], v[22:23], v[10:11] op_sel_hi:[1,0]
	v_pk_mul_f32 v[6:7], v[200:201], v[6:7]
	v_pk_mul_f32 v[6:7], v[6:7], v[20:21]
	v_rcp_f32_e32 v5, v5
	v_lshlrev_b32_e32 v20, 16, v195
	v_and_b32_e32 v21, 0xffff0000, v195
	v_mul_f32_e32 v3, 0xbfb8aa3b, v20
	v_exp_f32_e32 v22, v3
	v_mul_f32_e32 v3, 0xbfb8aa3b, v21
	v_exp_f32_e32 v23, v3
	v_rcp_f32_e32 v4, v4
	s_nop 0
	v_pk_mul_f32 v[2:3], v[4:5], v[6:7]
	v_pk_add_f32 v[4:5], v[22:23], 1.0 op_sel_hi:[1,0]
	v_cvt_pk_bf16_f32 v2, v2, v3
	v_pk_mul_f32 v[6:7], v[66:67], v[10:11] op_sel_hi:[1,0]
	v_pk_mul_f32 v[6:7], v[202:203], v[6:7]
	v_pk_mul_f32 v[6:7], v[6:7], v[20:21]
	v_rcp_f32_e32 v5, v5
	v_rcp_f32_e32 v4, v4
	s_nop 0
	v_pk_mul_f32 v[4:5], v[4:5], v[6:7]
	v_cvt_pk_bf16_f32 v3, v4, v5
	global_store_dwordx4 v[8:9], v[0:3], off offset:16
	s_waitcnt vmcnt(7)
	v_lshlrev_b32_e32 v56, 16, v204
	v_and_b32_e32 v57, 0xffff0000, v204
	v_mul_f32_e32 v0, 0xbfb8aa3b, v56
	v_exp_f32_e32 v58, v0
	v_mul_f32_e32 v0, 0xbfb8aa3b, v57
	v_exp_f32_e32 v59, v0
	s_nop 0
	v_pk_add_f32 v[58:59], v[58:59], 1.0 op_sel_hi:[1,0]
	v_pk_mul_f32 v[12:13], v[12:13], v[10:11] op_sel_hi:[1,0]
	v_pk_mul_f32 v[4:5], v[208:209], v[12:13]
	v_rcp_f32_e32 v13, v59
	v_pk_mul_f32 v[4:5], v[4:5], v[56:57]
	v_lshlrev_b32_e32 v56, 16, v205
	v_and_b32_e32 v57, 0xffff0000, v205
	v_mul_f32_e32 v1, 0xbfb8aa3b, v56
	v_exp_f32_e32 v60, v1
	v_mul_f32_e32 v1, 0xbfb8aa3b, v57
	v_exp_f32_e32 v61, v1
	v_rcp_f32_e32 v12, v58
	s_nop 0
	v_pk_mul_f32 v[0:1], v[12:13], v[4:5]
	v_pk_add_f32 v[4:5], v[60:61], 1.0 op_sel_hi:[1,0]
	v_cvt_pk_bf16_f32 v0, v0, v1
	v_pk_mul_f32 v[12:13], v[18:19], v[10:11] op_sel_hi:[1,0]
	v_pk_mul_f32 v[6:7], v[210:211], v[12:13]
	v_rcp_f32_e32 v5, v5
	v_pk_mul_f32 v[6:7], v[6:7], v[56:57]
	v_lshlrev_b32_e32 v12, 16, v206
	v_and_b32_e32 v13, 0xffff0000, v206
	v_mul_f32_e32 v2, 0xbfb8aa3b, v12
	v_exp_f32_e32 v18, v2
	v_mul_f32_e32 v2, 0xbfb8aa3b, v13
	v_exp_f32_e32 v19, v2
	v_rcp_f32_e32 v4, v4
	s_nop 0
	v_pk_mul_f32 v[4:5], v[4:5], v[6:7]
	v_cvt_pk_bf16_f32 v1, v4, v5
	v_pk_add_f32 v[4:5], v[18:19], 1.0 op_sel_hi:[1,0]
	v_pk_mul_f32 v[6:7], v[14:15], v[10:11] op_sel_hi:[1,0]
	v_pk_mul_f32 v[6:7], v[212:213], v[6:7]
	v_mov_b32_e32 v20, v51
	v_pk_mul_f32 v[6:7], v[6:7], v[12:13]
	v_rcp_f32_e32 v5, v5
	v_mov_b32_e32 v21, v53
	v_lshlrev_b32_e32 v12, 16, v207
	v_and_b32_e32 v13, 0xffff0000, v207
	v_mul_f32_e32 v3, 0xbfb8aa3b, v12
	v_exp_f32_e32 v14, v3
	v_mul_f32_e32 v3, 0xbfb8aa3b, v13
	v_exp_f32_e32 v15, v3
	v_rcp_f32_e32 v4, v4
	s_nop 0
	v_pk_mul_f32 v[2:3], v[4:5], v[6:7]
	v_mov_b32_e32 v51, v52
	v_pk_add_f32 v[4:5], v[14:15], 1.0 op_sel_hi:[1,0]
	v_cvt_pk_bf16_f32 v2, v2, v3
	v_pk_mul_f32 v[6:7], v[16:17], v[10:11] op_sel_hi:[1,0]
	v_pk_mul_f32 v[6:7], v[214:215], v[6:7]
	v_pk_mul_f32 v[6:7], v[6:7], v[12:13]
	v_rcp_f32_e32 v5, v5
	v_rcp_f32_e32 v4, v4
	s_nop 0
	v_pk_mul_f32 v[4:5], v[4:5], v[6:7]
	v_cvt_pk_bf16_f32 v3, v4, v5
	global_store_dwordx4 v[8:9], v[0:3], off offset:32
	s_waitcnt vmcnt(5)
	v_lshlrev_b32_e32 v16, 16, v216
	v_and_b32_e32 v17, 0xffff0000, v216
	v_mul_f32_e32 v0, 0xbfb8aa3b, v16
	v_exp_f32_e32 v18, v0
	v_mul_f32_e32 v0, 0xbfb8aa3b, v17
	v_exp_f32_e32 v19, v0
	s_nop 0
	v_pk_add_f32 v[18:19], v[18:19], 1.0 op_sel_hi:[1,0]
	v_pk_mul_f32 v[20:21], v[20:21], v[10:11] op_sel_hi:[1,0]
	v_pk_mul_f32 v[4:5], v[220:221], v[20:21]
	v_pk_mul_f32 v[4:5], v[4:5], v[16:17]
	v_rcp_f32_e32 v17, v19
	v_rcp_f32_e32 v16, v18
	s_nop 0
	v_pk_mul_f32 v[4:5], v[16:17], v[4:5]
	v_lshlrev_b32_e32 v16, 16, v217
	v_and_b32_e32 v17, 0xffff0000, v217
	v_mul_f32_e32 v0, 0xbfb8aa3b, v16
	v_exp_f32_e32 v18, v0
	v_mul_f32_e32 v0, 0xbfb8aa3b, v17
	v_exp_f32_e32 v19, v0
	v_cvt_pk_bf16_f32 v0, v4, v5
	v_mov_b32_e32 v4, v47
	v_mov_b32_e32 v5, v49
	v_pk_add_f32 v[18:19], v[18:19], 1.0 op_sel_hi:[1,0]
	v_mov_b32_e32 v47, v48
	v_pk_mul_f32 v[4:5], v[4:5], v[10:11] op_sel_hi:[1,0]
	v_pk_mul_f32 v[4:5], v[222:223], v[4:5]
	v_pk_mul_f32 v[4:5], v[4:5], v[16:17]
	v_rcp_f32_e32 v7, v19
	v_lshlrev_b32_e32 v16, 16, v218
	v_rcp_f32_e32 v6, v18
	v_and_b32_e32 v17, 0xffff0000, v218
	v_mul_f32_e32 v1, 0xbfb8aa3b, v16
	v_exp_f32_e32 v18, v1
	v_mul_f32_e32 v1, 0xbfb8aa3b, v17
	v_exp_f32_e32 v19, v1
	v_pk_mul_f32 v[4:5], v[6:7], v[4:5]
	v_cvt_pk_bf16_f32 v1, v4, v5
	v_pk_add_f32 v[4:5], v[18:19], 1.0 op_sel_hi:[1,0]
	v_pk_mul_f32 v[6:7], v[50:51], v[10:11] op_sel_hi:[1,0]
	v_pk_mul_f32 v[6:7], v[224:225], v[6:7]
	v_pk_mul_f32 v[6:7], v[6:7], v[16:17]
	v_rcp_f32_e32 v5, v5
	v_lshlrev_b32_e32 v12, 16, v219
	v_rcp_f32_e32 v4, v4
	v_and_b32_e32 v13, 0xffff0000, v219
	v_mul_f32_e32 v2, 0xbfb8aa3b, v12
	v_exp_f32_e32 v16, v2
	v_mul_f32_e32 v2, 0xbfb8aa3b, v13
	v_exp_f32_e32 v17, v2
	v_pk_mul_f32 v[2:3], v[4:5], v[6:7]
	v_pk_add_f32 v[4:5], v[16:17], 1.0 op_sel_hi:[1,0]
	v_cvt_pk_bf16_f32 v2, v2, v3
	v_pk_mul_f32 v[6:7], v[46:47], v[10:11] op_sel_hi:[1,0]
	v_pk_mul_f32 v[6:7], v[226:227], v[6:7]
	v_pk_mul_f32 v[6:7], v[6:7], v[12:13]
	v_rcp_f32_e32 v5, v5
	v_rcp_f32_e32 v4, v4
	s_nop 0
	v_pk_mul_f32 v[4:5], v[4:5], v[6:7]
	v_cmp_lt_i32_e32 vcc, s18, v24
	v_cvt_pk_bf16_f32 v3, v4, v5
	s_or_b64 s[8:9], vcc, s[8:9]
	global_store_dwordx4 v[8:9], v[0:3], off offset:48
	s_andn2_b64 exec, exec, s[8:9]
	s_cbranch_execnz .LBB0_513

; __device__ __forceinline__ void gemm_prologue(const u16* __restrict__ A, const u16* __restrict__ Bt, const int K,
;                                               const int brow, const int bcol) {
;   int tid = threadIdx.x;
;   asm volatile("" : "+v"(tid));
;   const int tid16 = tid * 16;
;   int goff0, goff1;
;   { int R, C; stage_rc(tid16, R, C); goff0 = R * K + C; stage_rc(tid16 + 8192, R, C); goff1 = R * K + C; }
;   STAGE(SB(0, 0), Bt, bcol, 0); STAGE(SA(0, 0), A, brow, 0);
;   STAGE(SB(0, 1), Bt, bcol + HALF, 0); STAGE(SA(0, 1), A, brow + HALF, 0);
; __device__ void phase3(const Params& p) {
;     ...
;     gemm_prologue(p.YB, p.WupbT, 2048, brow, bcol);
;     const char* gta = p.GT + (size_t)((pm * 16 + pn) * 2) * 131072 + tid * 16;
;     const char* gtb = gta + 131072;
;     {
;       int koff = 0;
; #pragma unroll
;       for (int ai = 0; ai < 2; ++ai)
; #pragma unroll
;         for (int bj = 0; bj < 2; ++bj) {
;           asm volatile("" : "+v"(koff));
;           u32x4 sa[4], sb[4];
; #pragma unroll
;           for (int m = 0; m < 4; ++m) {
;             sa[m] = __builtin_nontemporal_load((const u32x4*)(gta + koff + ((ai * 2 + bj) * 4 + m) * 8192));
;             sb[m] = __builtin_nontemporal_load((const u32x4*)(gtb + koff + ((ai * 2 + bj) * 4 + m) * 8192));
;           }
.LBB0_562:
	s_or_b64 exec, exec, s[56:57]
	v_mov_b32_e32 v124, v248
	s_waitcnt vmcnt(0)
	s_barrier
	s_lshl_b64 s[48:49], s[48:49], 1
	v_ashrrev_i32_e32 v125, 31, v124
	v_lshrrev_b32_e32 v125, 26, v125
	v_lshlrev_b32_e32 v130, 4, v124
	v_add_u32_e32 v125, v124, v125
	v_bfe_i32 v124, v124, 27, 1
	v_lshrrev_b32_e32 v124, 22, v124
	v_add_u32_e32 v124, v130, v124
	v_and_b32_e32 v124, 0xfffffc00, v124
	v_sub_u32_e32 v124, v130, v124
	v_lshrrev_b32_e32 v126, 4, v124
	v_bitop3_b32 v124, v126, v124, 32 bitop3:0x6c
	v_ashrrev_i32_e32 v127, 31, v124
	v_ashrrev_i32_e32 v125, 6, v125
	v_lshrrev_b32_e32 v127, 26, v127
	v_lshlrev_b32_e32 v126, 3, v125
	v_add_u32_e32 v127, v124, v127
	v_and_b32_e32 v126, 0x1ffff0, v126
	v_lshrrev_b32_e32 v128, 6, v127
	v_lshlrev_b32_e32 v125, 5, v125
	v_and_b32_e32 v127, 0xc0, v127
	v_add_u32_e32 v126, v128, v126
	v_and_b32_e32 v125, 32, v125
	v_sub_u32_e32 v124, v124, v127
	v_ashrrev_i16_sdwa v124, v251, sext(v124) dst_sel:DWORD dst_unused:UNUSED_PAD src0_sel:DWORD src1_sel:BYTE_0
	v_lshl_or_b32 v125, v126, 11, v125
	v_add_u32_e32 v131, 0x2000, v130
	v_add_u32_sdwa v124, v125, sext(v124) dst_sel:DWORD dst_unused:UNUSED_PAD src0_sel:DWORD src1_sel:WORD_0
	v_ashrrev_i32_e32 v125, 31, v131
	v_lshrrev_b32_e32 v125, 22, v125
	v_add_u32_e32 v125, v131, v125
	v_ashrrev_i32_e32 v125, 10, v125
	v_mul_i32_i24_e32 v126, 0x400, v125
	v_sub_u32_e32 v126, v131, v126
	v_lshrrev_b32_e32 v127, 4, v126
	v_bitop3_b32 v126, v127, v126, 32 bitop3:0x6c
	v_ashrrev_i32_e32 v128, 31, v126
	v_lshrrev_b32_e32 v128, 26, v128
	v_lshlrev_b32_e32 v127, 3, v125
	v_add_u32_e32 v128, v126, v128
	v_and_b32_e32 v127, 0x1ffff0, v127
	v_lshrrev_b32_e32 v129, 6, v128
	v_lshlrev_b32_e32 v125, 5, v125
	v_and_b32_e32 v128, 0xc0, v128
	v_add_u32_e32 v127, v129, v127
	v_and_b32_e32 v125, 32, v125
	v_sub_u32_e32 v126, v126, v128
	v_ashrrev_i16_sdwa v126, v251, sext(v126) dst_sel:DWORD dst_unused:UNUSED_PAD src0_sel:DWORD src1_sel:BYTE_0
	v_lshl_or_b32 v125, v127, 11, v125
	v_add_u32_sdwa v126, v125, sext(v126) dst_sel:DWORD dst_unused:UNUSED_PAD src0_sel:DWORD src1_sel:WORD_0
	s_add_u32 s56, s68, s48
	v_ashrrev_i32_e32 v125, 31, v124
	v_add_u32_e32 v127, 0x10000, v130
	s_addc_u32 s57, s69, s49
	v_lshlrev_b64 v[124:125], 1, v[124:125]
	v_readfirstlane_b32 s48, v127
	v_ashrrev_i32_e32 v127, 31, v126
	v_add_u32_e32 v132, 0x12000, v130
	s_lshl_b32 s5, s5, 1
	v_lshl_add_u64 v[128:129], s[56:57], 0, v[124:125]
	s_mov_b32 m0, s48
	v_lshlrev_b64 v[126:127], 1, v[126:127]
	v_readfirstlane_b32 s48, v132
	s_add_u32 s58, s78, s5
	global_load_lds_dwordx4 v[128:129], off
	v_lshl_add_u64 v[128:129], s[56:57], 0, v[126:127]
	s_mov_b32 m0, s48
	s_addc_u32 s59, s79, 0
	v_readfirstlane_b32 s5, v130
	s_lshl_b64 s[48:49], s[60:61], 1
	global_load_lds_dwordx4 v[128:129], off
	v_lshl_add_u64 v[128:129], s[58:59], 0, v[124:125]
	s_mov_b32 m0, s5
	v_readfirstlane_b32 s5, v131
	s_add_u32 s60, s68, s48
	v_add_u32_e32 v131, 0x14000, v130
	global_load_lds_dwordx4 v[128:129], off
	v_lshl_add_u64 v[128:129], s[58:59], 0, v[126:127]
	s_mov_b32 m0, s5
	s_addc_u32 s61, s69, s49
	v_readfirstlane_b32 s5, v131
	v_add_u32_e32 v131, 0x16000, v130
	global_load_lds_dwordx4 v[128:129], off
	v_lshl_add_u64 v[128:129], s[60:61], 0, v[124:125]
	s_mov_b32 m0, s5
	v_readfirstlane_b32 s5, v131
	global_load_lds_dwordx4 v[128:129], off
	v_lshl_add_u64 v[128:129], s[60:61], 0, v[126:127]
	s_mov_b32 m0, s5
	s_lshl_b32 s5, s63, 1
	global_load_lds_dwordx4 v[128:129], off
	s_add_u32 s48, s78, s5
	v_add_u32_e32 v128, 0x4000, v130
	s_addc_u32 s49, s79, 0
	v_readfirstlane_b32 s5, v128
	v_lshl_add_u64 v[124:125], s[48:49], 0, v[124:125]
	s_mov_b32 m0, s5
	s_lshl_b32 s62, s62, 1
	global_load_lds_dwordx4 v[124:125], off
	v_lshl_add_u64 v[124:125], s[48:49], 0, v[126:127]
	v_add_u32_e32 v126, 0x6000, v130
	v_mov_b32_e32 v166, 0
	v_readfirstlane_b32 s5, v126
	s_mov_b32 m0, s5
	s_lshl_b32 s5, s2, 5
	s_add_i32 s62, s5, s62
	s_ashr_i32 s63, s62, 31
	s_lshl_b64 s[62:63], s[62:63], 17
	global_load_lds_dwordx4 v[124:125], off
	v_lshl_add_u64 v[132:133], v[244:245], 0, s[62:63]
	v_lshl_add_u64 v[246:247], v[132:133], 0, s[30:31]
	v_ashrrev_i32_e32 v167, 31, v166
	v_lshl_add_u64 v[124:125], v[132:133], 0, v[166:167]
	v_lshl_add_u64 v[128:129], v[246:247], 0, v[166:167]
	s_mov_b32 s101, 0
	global_load_dwordx4 v[204:207], v[132:133], off nt
	global_load_dwordx4 v[200:203], v[246:247], off nt
	s_mov_b32 s100, s64
	v_lshl_add_u64 v[228:229], v[132:133], 0, s[100:101]
	global_load_dwordx4 v[174:177], v[228:229], off nt
	s_mov_b32 s100, s64
	v_lshl_add_u64 v[228:229], v[246:247], 0, s[100:101]
	global_load_dwordx4 v[178:181], v[228:229], off nt
	s_mov_b32 s100, s87
	v_lshl_add_u64 v[228:229], v[132:133], 0, s[100:101]
	global_load_dwordx4 v[140:143], v[228:229], off nt
	s_mov_b32 s100, s87
	v_lshl_add_u64 v[228:229], v[246:247], 0, s[100:101]
	global_load_dwordx4 v[144:147], v[228:229], off nt
	s_mov_b32 s100, s88
	v_lshl_add_u64 v[228:229], v[132:133], 0, s[100:101]
	global_load_dwordx4 v[124:127], v[228:229], off nt
	s_mov_b32 s100, s88
	v_lshl_add_u64 v[228:229], v[246:247], 0, s[100:101]
	global_load_dwordx4 v[128:131], v[228:229], off nt
	s_mov_b32 s100, s67
	v_lshl_add_u64 v[228:229], v[132:133], 0, s[100:101]
	global_load_dwordx4 v[214:217], v[228:229], off nt
	s_mov_b32 s100, s67
	v_lshl_add_u64 v[228:229], v[246:247], 0, s[100:101]
	global_load_dwordx4 v[218:221], v[228:229], off nt
	s_mov_b32 s100, s72
	v_lshl_add_u64 v[228:229], v[132:133], 0, s[100:101]
	global_load_dwordx4 v[188:191], v[228:229], off nt
	s_mov_b32 s100, s72
	v_lshl_add_u64 v[228:229], v[246:247], 0, s[100:101]
	global_load_dwordx4 v[192:195], v[228:229], off nt
	s_mov_b32 s100, s81
	v_lshl_add_u64 v[228:229], v[132:133], 0, s[100:101]
	global_load_dwordx4 v[158:161], v[228:229], off nt
	s_mov_b32 s100, s81
	v_lshl_add_u64 v[228:229], v[246:247], 0, s[100:101]
	global_load_dwordx4 v[162:165], v[228:229], off nt
	s_waitcnt vmcnt(13)
; __device__ __forceinline__ float bflo(u32 v) { return __uint_as_float(v << 16); }
; __device__ __forceinline__ float bfhi(u32 v) { return __uint_as_float(v & 0xffff0000u); }
; __device__ void phase3(const Params& p) {
;     ...
;           asm volatile("" : "+v"(koff));
;           u32x4 sa[4], sb[4];
; #pragma unroll
;           for (int m = 0; m < 4; ++m) {
;             sa[m] = __builtin_nontemporal_load((const u32x4*)(gta + koff + ((ai * 2 + bj) * 4 + m) * 8192));
;             sb[m] = __builtin_nontemporal_load((const u32x4*)(gtb + koff + ((ai * 2 + bj) * 4 + m) * 8192));
;           }
; #pragma unroll
;           for (int m = 0; m < 4; ++m)
; #pragma unroll
;             for (int n = 0; n < 2; ++n) {
;               const u32x4 A4 = sa[m], B4 = sb[m];
;               acc[ai][bj][m][n][0] *= bflo(A4[2 * n]) / bflo(B4[2 * n]);
;               acc[ai][bj][m][n][1] *= bfhi(A4[2 * n]) / bfhi(B4[2 * n]);
;               acc[ai][bj][m][n][2] *= bflo(A4[2 * n + 1]) / bflo(B4[2 * n + 1]);
;               acc[ai][bj][m][n][3] *= bfhi(A4[2 * n + 1]) / bfhi(B4[2 * n + 1]);
;             }
;           asm volatile("" : "+v"(acc[ai][bj][0][0]), "+v"(acc[ai][bj][1][1]), "+v"(acc[ai][bj][2][0]), "+v"(acc[ai][bj][3][1]));
	v_and_b32_e32 v135, 0xffff0000, v204
	s_waitcnt vmcnt(12)
	v_and_b32_e32 v137, 0xffff0000, v200
	v_lshlrev_b32_e32 v134, 16, v204
	v_lshlrev_b32_e32 v136, 16, v200
	v_rcp_f32_e32 v138, v137
	s_nop 0
	v_mul_f32_e32 v135, v135, v138
	v_rcp_f32_e32 v137, v136
	s_nop 0
	v_mul_f32_e32 v134, v134, v137
	v_pk_mul_f32 v[0:1], v[0:1], v[134:135]
	v_and_b32_e32 v135, 0xffff0000, v205
	v_and_b32_e32 v137, 0xffff0000, v201
	v_lshlrev_b32_e32 v134, 16, v205
	v_lshlrev_b32_e32 v136, 16, v201
	v_rcp_f32_e32 v138, v137
	s_nop 0
	v_mul_f32_e32 v135, v135, v138
	v_rcp_f32_e32 v137, v136
	s_nop 0
	v_mul_f32_e32 v134, v134, v137
	v_pk_mul_f32 v[2:3], v[2:3], v[134:135]
	s_waitcnt vmcnt(11)
	v_and_b32_e32 v135, 0xffff0000, v176
	s_waitcnt vmcnt(10)
	v_and_b32_e32 v137, 0xffff0000, v180
	v_lshlrev_b32_e32 v134, 16, v176
	v_lshlrev_b32_e32 v136, 16, v180
	v_rcp_f32_e32 v138, v137
	s_nop 0
	v_mul_f32_e32 v135, v135, v138
	v_rcp_f32_e32 v137, v136
	s_nop 0
	v_mul_f32_e32 v134, v134, v137
	v_pk_mul_f32 v[4:5], v[4:5], v[134:135]
	v_and_b32_e32 v135, 0xffff0000, v177
	v_and_b32_e32 v137, 0xffff0000, v181
	v_lshlrev_b32_e32 v134, 16, v177
	v_lshlrev_b32_e32 v136, 16, v181
	v_rcp_f32_e32 v138, v137
	s_nop 0
	v_mul_f32_e32 v135, v135, v138
	v_rcp_f32_e32 v137, v136
	s_nop 0
	v_mul_f32_e32 v134, v134, v137
	v_pk_mul_f32 v[6:7], v[6:7], v[134:135]
	s_waitcnt vmcnt(9)
	v_and_b32_e32 v135, 0xffff0000, v140
	s_waitcnt vmcnt(8)
	v_and_b32_e32 v137, 0xffff0000, v144
	v_lshlrev_b32_e32 v134, 16, v140
	v_lshlrev_b32_e32 v136, 16, v144
	v_rcp_f32_e32 v138, v137
	s_nop 0
	v_mul_f32_e32 v135, v135, v138
	v_rcp_f32_e32 v137, v136
	s_nop 0
	v_mul_f32_e32 v134, v134, v137
	v_pk_mul_f32 v[8:9], v[8:9], v[134:135]
	v_and_b32_e32 v135, 0xffff0000, v141
	v_and_b32_e32 v137, 0xffff0000, v145
	v_lshlrev_b32_e32 v134, 16, v141
	v_lshlrev_b32_e32 v136, 16, v145
	v_rcp_f32_e32 v138, v137
	s_nop 0
	v_mul_f32_e32 v135, v135, v138
	v_rcp_f32_e32 v137, v136
	s_nop 0
	v_mul_f32_e32 v134, v134, v137
	v_pk_mul_f32 v[10:11], v[10:11], v[134:135]
	s_waitcnt vmcnt(7)
	v_lshlrev_b32_e32 v134, 16, v126
	v_and_b32_e32 v126, 0xffff0000, v126
	s_waitcnt vmcnt(6)
	v_lshlrev_b32_e32 v136, 16, v130
	v_and_b32_e32 v130, 0xffff0000, v130
	v_rcp_f32_e32 v135, v130
	s_nop 0
	v_mul_f32_e32 v135, v126, v135
	v_rcp_f32_e32 v126, v136
	s_nop 0
	v_mul_f32_e32 v134, v134, v126
	v_lshlrev_b32_e32 v126, 16, v127
	v_and_b32_e32 v127, 0xffff0000, v127
	v_lshlrev_b32_e32 v130, 16, v131
	v_and_b32_e32 v131, 0xffff0000, v131
	v_pk_mul_f32 v[12:13], v[12:13], v[134:135]
	v_rcp_f32_e32 v134, v131
	s_nop 0
	v_mul_f32_e32 v127, v127, v134
	v_rcp_f32_e32 v131, v130
	s_nop 0
	v_mul_f32_e32 v126, v126, v131
	v_pk_mul_f32 v[14:15], v[14:15], v[126:127]
	v_ashrrev_i32_e32 v167, 31, v166
	s_mov_b32 s100, s84
	v_lshl_add_u64 v[222:223], v[132:133], 0, s[100:101]
	global_load_dwordx4 v[134:137], v[222:223], off nt
	s_mov_b32 s100, s84
	v_lshl_add_u64 v[222:223], v[246:247], 0, s[100:101]
	global_load_dwordx4 v[138:141], v[222:223], off nt
	s_mov_b32 s100, s75
	v_lshl_add_u64 v[222:223], v[132:133], 0, s[100:101]
	global_load_dwordx4 v[228:231], v[222:223], off nt
	s_mov_b32 s100, s75
	v_lshl_add_u64 v[222:223], v[246:247], 0, s[100:101]
	global_load_dwordx4 v[232:235], v[222:223], off nt
	s_mov_b32 s100, s85
	v_lshl_add_u64 v[222:223], v[132:133], 0, s[100:101]
	global_load_dwordx4 v[208:211], v[222:223], off nt
	s_mov_b32 s100, s80
	v_lshl_add_u64 v[222:223], v[132:133], 0, s[100:101]
	global_load_dwordx4 v[180:183], v[222:223], off nt
	s_mov_b32 s100, s80
	v_lshl_add_u64 v[222:223], v[246:247], 0, s[100:101]
	global_load_dwordx4 v[184:187], v[222:223], off nt
	s_mov_b32 s100, s86
	v_lshl_add_u64 v[222:223], v[132:133], 0, s[100:101]
	global_load_dwordx4 v[152:155], v[222:223], off nt
	s_nop 1
	s_nop 1
	s_nop 1
	s_nop 1
	s_nop 1
	s_waitcnt vmcnt(12)
	v_lshlrev_b32_e32 v130, 16, v218
	v_and_b32_e32 v127, 0xffff0000, v214
	v_and_b32_e32 v131, 0xffff0000, v218
	v_lshlrev_b32_e32 v126, 16, v214
	v_rcp_f32_e32 v144, v131
	s_nop 0
	v_mul_f32_e32 v127, v127, v144
	v_rcp_f32_e32 v131, v130
	s_nop 0
	v_mul_f32_e32 v126, v126, v131
	v_pk_mul_f32 v[20:21], v[20:21], v[126:127]
	v_and_b32_e32 v127, 0xffff0000, v215
	v_and_b32_e32 v131, 0xffff0000, v219
	v_lshlrev_b32_e32 v126, 16, v215
	v_lshlrev_b32_e32 v130, 16, v219
	v_rcp_f32_e32 v144, v131
	s_nop 0
	v_mul_f32_e32 v127, v127, v144
	v_rcp_f32_e32 v131, v130
	s_nop 0
	v_mul_f32_e32 v126, v126, v131
	v_pk_mul_f32 v[22:23], v[22:23], v[126:127]
	s_waitcnt vmcnt(11)
	v_and_b32_e32 v127, 0xffff0000, v190
	s_waitcnt vmcnt(10)
	v_and_b32_e32 v131, 0xffff0000, v194
	v_lshlrev_b32_e32 v126, 16, v190
	v_lshlrev_b32_e32 v130, 16, v194
	v_rcp_f32_e32 v144, v131
	s_nop 0
	v_mul_f32_e32 v127, v127, v144
	v_rcp_f32_e32 v131, v130
	s_nop 0
	v_mul_f32_e32 v126, v126, v131
	v_pk_mul_f32 v[28:29], v[28:29], v[126:127]
	v_and_b32_e32 v127, 0xffff0000, v191
	v_and_b32_e32 v131, 0xffff0000, v195
	v_lshlrev_b32_e32 v126, 16, v191
	v_lshlrev_b32_e32 v130, 16, v195
	v_rcp_f32_e32 v144, v131
	s_nop 0
	v_mul_f32_e32 v127, v127, v144
	v_rcp_f32_e32 v131, v130
	s_nop 0
	v_mul_f32_e32 v126, v126, v131
	v_pk_mul_f32 v[30:31], v[30:31], v[126:127]
	s_waitcnt vmcnt(9)
	v_and_b32_e32 v127, 0xffff0000, v158
	s_waitcnt vmcnt(8)
	v_and_b32_e32 v131, 0xffff0000, v162
	v_lshlrev_b32_e32 v126, 16, v158
	v_lshlrev_b32_e32 v130, 16, v162
	v_rcp_f32_e32 v144, v131
	s_nop 0
	v_mul_f32_e32 v127, v127, v144
	v_rcp_f32_e32 v131, v130
	s_nop 0
	v_mul_f32_e32 v126, v126, v131
	v_pk_mul_f32 v[36:37], v[36:37], v[126:127]
	v_and_b32_e32 v127, 0xffff0000, v159
	v_and_b32_e32 v131, 0xffff0000, v163
	v_lshlrev_b32_e32 v126, 16, v159
	v_lshlrev_b32_e32 v130, 16, v163
	v_rcp_f32_e32 v144, v131
	s_nop 0
	v_mul_f32_e32 v127, v127, v144
	v_rcp_f32_e32 v131, v130
	s_nop 0
	v_mul_f32_e32 v126, v126, v131
	v_pk_mul_f32 v[38:39], v[38:39], v[126:127]
	s_waitcnt vmcnt(7)
; __device__ __forceinline__ float bflo(u32 v) { return __uint_as_float(v << 16); }
; __device__ __forceinline__ float bfhi(u32 v) { return __uint_as_float(v & 0xffff0000u); }
; __device__ void phase3(const Params& p) {
;     ...
;           asm volatile("" : "+v"(koff));
;           u32x4 sa[4], sb[4];
; #pragma unroll
;           for (int m = 0; m < 4; ++m) {
;             sa[m] = __builtin_nontemporal_load((const u32x4*)(gta + koff + ((ai * 2 + bj) * 4 + m) * 8192));
;             sb[m] = __builtin_nontemporal_load((const u32x4*)(gtb + koff + ((ai * 2 + bj) * 4 + m) * 8192));
;           }
; #pragma unroll
;           for (int m = 0; m < 4; ++m)
; #pragma unroll
;             for (int n = 0; n < 2; ++n) {
;               const u32x4 A4 = sa[m], B4 = sb[m];
;               acc[ai][bj][m][n][0] *= bflo(A4[2 * n]) / bflo(B4[2 * n]);
;               acc[ai][bj][m][n][1] *= bfhi(A4[2 * n]) / bfhi(B4[2 * n]);
;               acc[ai][bj][m][n][2] *= bflo(A4[2 * n + 1]) / bflo(B4[2 * n + 1]);
;               acc[ai][bj][m][n][3] *= bfhi(A4[2 * n + 1]) / bfhi(B4[2 * n + 1]);
;             }
;           asm volatile("" : "+v"(acc[ai][bj][0][0]), "+v"(acc[ai][bj][1][1]), "+v"(acc[ai][bj][2][0]), "+v"(acc[ai][bj][3][1]));
	v_and_b32_e32 v127, 0xffff0000, v136
	s_waitcnt vmcnt(6)
	v_and_b32_e32 v131, 0xffff0000, v140
	v_lshlrev_b32_e32 v126, 16, v136
	v_lshlrev_b32_e32 v130, 16, v140
	v_rcp_f32_e32 v136, v131
	s_nop 0
	v_mul_f32_e32 v127, v127, v136
	v_rcp_f32_e32 v131, v130
	s_nop 0
	v_mul_f32_e32 v126, v126, v131
	v_pk_mul_f32 v[44:45], v[44:45], v[126:127]
	v_and_b32_e32 v127, 0xffff0000, v137
	v_and_b32_e32 v131, 0xffff0000, v141
	v_lshlrev_b32_e32 v126, 16, v137
	v_lshlrev_b32_e32 v130, 16, v141
	v_rcp_f32_e32 v136, v131
	s_nop 0
	v_mul_f32_e32 v127, v127, v136
	v_rcp_f32_e32 v131, v130
	s_nop 0
	v_mul_f32_e32 v126, v126, v131
	v_pk_mul_f32 v[46:47], v[46:47], v[126:127]
	v_ashrrev_i32_e32 v167, 31, v166
	s_mov_b32 s100, s85
	v_lshl_add_u64 v[168:169], v[246:247], 0, s[100:101]
	global_load_dwordx4 v[212:215], v[168:169], off nt
	s_mov_b32 s100, s86
	v_lshl_add_u64 v[168:169], v[246:247], 0, s[100:101]
	global_load_dwordx4 v[156:159], v[168:169], off nt
	s_mov_b32 s100, s65
	v_lshl_add_u64 v[168:169], v[132:133], 0, s[100:101]
	global_load_dwordx4 v[236:239], v[168:169], off nt
	s_mov_b32 s100, s65
	v_lshl_add_u64 v[168:169], v[246:247], 0, s[100:101]
	global_load_dwordx4 v[240:243], v[168:169], off nt
	s_mov_b32 s100, s66
	v_lshl_add_u64 v[168:169], v[132:133], 0, s[100:101]
	global_load_dwordx4 v[222:225], v[168:169], off nt
	s_mov_b32 s100, s73
	v_lshl_add_u64 v[168:169], v[132:133], 0, s[100:101]
	global_load_dwordx4 v[194:197], v[168:169], off nt
	s_mov_b32 s100, s73
	v_lshl_add_u64 v[168:169], v[246:247], 0, s[100:101]
	global_load_dwordx4 v[198:201], v[168:169], off nt
	s_mov_b32 s100, s74
	v_lshl_add_u64 v[168:169], v[246:247], 0, s[100:101]
	global_load_dwordx4 v[170:173], v[168:169], off nt
	s_nop 1
	s_nop 1
	s_nop 1
	s_nop 1
	s_nop 1
	s_waitcnt vmcnt(12)
	v_lshlrev_b32_e32 v130, 16, v232
	v_and_b32_e32 v127, 0xffff0000, v228
	v_and_b32_e32 v131, 0xffff0000, v232
	v_lshlrev_b32_e32 v126, 16, v228
	v_rcp_f32_e32 v136, v131
	s_nop 0
	v_mul_f32_e32 v127, v127, v136
	v_rcp_f32_e32 v131, v130
	s_nop 0
	v_mul_f32_e32 v126, v126, v131
	v_pk_mul_f32 v[52:53], v[52:53], v[126:127]
	v_and_b32_e32 v127, 0xffff0000, v229
	v_and_b32_e32 v131, 0xffff0000, v233
	v_lshlrev_b32_e32 v126, 16, v229
	v_lshlrev_b32_e32 v130, 16, v233
	v_rcp_f32_e32 v136, v131
	s_nop 0
	v_mul_f32_e32 v127, v127, v136
	v_rcp_f32_e32 v131, v130
	s_nop 0
	v_mul_f32_e32 v126, v126, v131
	v_pk_mul_f32 v[54:55], v[54:55], v[126:127]
	s_waitcnt vmcnt(11)
	v_and_b32_e32 v127, 0xffff0000, v210
	s_waitcnt vmcnt(7)
	v_and_b32_e32 v131, 0xffff0000, v214
	v_lshlrev_b32_e32 v126, 16, v210
	v_lshlrev_b32_e32 v130, 16, v214
	v_rcp_f32_e32 v136, v131
	s_nop 0
	v_mul_f32_e32 v127, v127, v136
	v_rcp_f32_e32 v131, v130
	s_nop 0
	v_mul_f32_e32 v126, v126, v131
	v_pk_mul_f32 v[60:61], v[60:61], v[126:127]
	v_and_b32_e32 v127, 0xffff0000, v211
	v_and_b32_e32 v131, 0xffff0000, v215
	v_lshlrev_b32_e32 v126, 16, v211
	v_lshlrev_b32_e32 v130, 16, v215
	v_rcp_f32_e32 v136, v131
	s_nop 0
	v_mul_f32_e32 v127, v127, v136
	v_rcp_f32_e32 v131, v130
	s_nop 0
	v_mul_f32_e32 v126, v126, v131
	v_pk_mul_f32 v[62:63], v[62:63], v[126:127]
	v_and_b32_e32 v127, 0xffff0000, v180
	v_and_b32_e32 v131, 0xffff0000, v184
	v_lshlrev_b32_e32 v126, 16, v180
	v_lshlrev_b32_e32 v130, 16, v184
	v_rcp_f32_e32 v136, v131
	s_nop 0
	v_mul_f32_e32 v127, v127, v136
	v_rcp_f32_e32 v131, v130
	s_nop 0
	v_mul_f32_e32 v126, v126, v131
	v_pk_mul_f32 v[68:69], v[68:69], v[126:127]
	v_and_b32_e32 v127, 0xffff0000, v181
	v_and_b32_e32 v131, 0xffff0000, v185
	v_lshlrev_b32_e32 v126, 16, v181
	v_lshlrev_b32_e32 v130, 16, v185
	v_rcp_f32_e32 v136, v131
	s_nop 0
	v_mul_f32_e32 v127, v127, v136
	v_rcp_f32_e32 v131, v130
	s_nop 0
	v_mul_f32_e32 v126, v126, v131
	v_pk_mul_f32 v[70:71], v[70:71], v[126:127]
	v_and_b32_e32 v127, 0xffff0000, v154
	s_waitcnt vmcnt(6)
; __device__ __forceinline__ float bflo(u32 v) { return __uint_as_float(v << 16); }
; __device__ __forceinline__ float bfhi(u32 v) { return __uint_as_float(v & 0xffff0000u); }
; #define BAR __builtin_amdgcn_s_barrier()
; __device__ __forceinline__ void gemm_main(const u16* __restrict__ A, const u16* __restrict__ Bt, const int K, const int Klen,
;                                           const int brow, const int bcol, f32x4 (&acc)[2][2][4][2]) {
;     ...
;   if (wr == 1) BAR;
; __device__ void phase3(const Params& p) {
;     ...
;           asm volatile("" : "+v"(koff));
;           u32x4 sa[4], sb[4];
; #pragma unroll
;           for (int m = 0; m < 4; ++m) {
;             sa[m] = __builtin_nontemporal_load((const u32x4*)(gta + koff + ((ai * 2 + bj) * 4 + m) * 8192));
;             sb[m] = __builtin_nontemporal_load((const u32x4*)(gtb + koff + ((ai * 2 + bj) * 4 + m) * 8192));
;           }
; #pragma unroll
;           for (int m = 0; m < 4; ++m)
; #pragma unroll
;             for (int n = 0; n < 2; ++n) {
;               const u32x4 A4 = sa[m], B4 = sb[m];
;               acc[ai][bj][m][n][0] *= bflo(A4[2 * n]) / bflo(B4[2 * n]);
;               acc[ai][bj][m][n][1] *= bfhi(A4[2 * n]) / bfhi(B4[2 * n]);
;               acc[ai][bj][m][n][2] *= bflo(A4[2 * n + 1]) / bflo(B4[2 * n + 1]);
;               acc[ai][bj][m][n][3] *= bfhi(A4[2 * n + 1]) / bfhi(B4[2 * n + 1]);
;             }
;           asm volatile("" : "+v"(acc[ai][bj][0][0]), "+v"(acc[ai][bj][1][1]), "+v"(acc[ai][bj][2][0]), "+v"(acc[ai][bj][3][1]));
	v_and_b32_e32 v131, 0xffff0000, v158
	v_lshlrev_b32_e32 v126, 16, v154
	v_lshlrev_b32_e32 v130, 16, v158
	v_rcp_f32_e32 v136, v131
	s_nop 0
	v_mul_f32_e32 v127, v127, v136
	v_rcp_f32_e32 v131, v130
	s_nop 0
	v_mul_f32_e32 v126, v126, v131
	v_pk_mul_f32 v[76:77], v[76:77], v[126:127]
	v_and_b32_e32 v127, 0xffff0000, v155
	v_and_b32_e32 v131, 0xffff0000, v159
	v_lshlrev_b32_e32 v126, 16, v155
	v_lshlrev_b32_e32 v130, 16, v159
	v_rcp_f32_e32 v136, v131
	s_nop 0
	v_mul_f32_e32 v127, v127, v136
	v_rcp_f32_e32 v131, v130
	s_nop 0
	v_mul_f32_e32 v126, v126, v131
	v_pk_mul_f32 v[78:79], v[78:79], v[126:127]
	v_ashrrev_i32_e32 v167, 31, v166
	s_mov_b32 s100, s66
	v_lshl_add_u64 v[168:169], v[246:247], 0, s[100:101]
	global_load_dwordx4 v[226:229], v[168:169], off nt
	s_mov_b32 s100, s74
	v_lshl_add_u64 v[168:169], v[132:133], 0, s[100:101]
	global_load_dwordx4 v[166:169], v[168:169], off nt
	s_nop 1
	s_nop 1
	s_nop 1
	s_nop 1
	s_nop 1
	s_waitcnt vmcnt(6)
	v_lshlrev_b32_e32 v130, 16, v240
	v_and_b32_e32 v127, 0xffff0000, v236
	v_and_b32_e32 v131, 0xffff0000, v240
	v_lshlrev_b32_e32 v126, 16, v236
	v_rcp_f32_e32 v132, v131
	s_nop 0
	v_mul_f32_e32 v127, v127, v132
	v_rcp_f32_e32 v131, v130
	s_nop 0
	v_mul_f32_e32 v126, v126, v131
	v_pk_mul_f32 v[88:89], v[88:89], v[126:127]
	v_and_b32_e32 v127, 0xffff0000, v237
	v_and_b32_e32 v131, 0xffff0000, v241
	v_lshlrev_b32_e32 v126, 16, v237
	v_lshlrev_b32_e32 v130, 16, v241
	v_rcp_f32_e32 v132, v131
	s_nop 0
	v_mul_f32_e32 v127, v127, v132
	v_rcp_f32_e32 v131, v130
	s_nop 0
	v_mul_f32_e32 v126, v126, v131
	v_pk_mul_f32 v[90:91], v[90:91], v[126:127]
	s_waitcnt vmcnt(5)
	v_and_b32_e32 v127, 0xffff0000, v224
	s_waitcnt vmcnt(1)
	v_and_b32_e32 v131, 0xffff0000, v228
	v_lshlrev_b32_e32 v126, 16, v224
	v_lshlrev_b32_e32 v130, 16, v228
	v_rcp_f32_e32 v132, v131
	s_nop 0
	v_mul_f32_e32 v127, v127, v132
	v_rcp_f32_e32 v131, v130
	s_nop 0
	v_mul_f32_e32 v126, v126, v131
	v_pk_mul_f32 v[96:97], v[96:97], v[126:127]
	v_and_b32_e32 v127, 0xffff0000, v225
	v_and_b32_e32 v131, 0xffff0000, v229
	v_lshlrev_b32_e32 v126, 16, v225
	v_lshlrev_b32_e32 v130, 16, v229
	v_rcp_f32_e32 v132, v131
	s_nop 0
	v_mul_f32_e32 v127, v127, v132
	v_rcp_f32_e32 v131, v130
	s_nop 0
	v_mul_f32_e32 v126, v126, v131
	v_pk_mul_f32 v[98:99], v[98:99], v[126:127]
	v_and_b32_e32 v127, 0xffff0000, v194
	v_and_b32_e32 v131, 0xffff0000, v198
	v_lshlrev_b32_e32 v126, 16, v194
	v_lshlrev_b32_e32 v130, 16, v198
	v_rcp_f32_e32 v132, v131
	s_nop 0
	v_mul_f32_e32 v127, v127, v132
	v_rcp_f32_e32 v131, v130
	s_nop 0
	v_mul_f32_e32 v126, v126, v131
	v_pk_mul_f32 v[104:105], v[104:105], v[126:127]
	v_and_b32_e32 v127, 0xffff0000, v195
	v_and_b32_e32 v131, 0xffff0000, v199
	v_lshlrev_b32_e32 v126, 16, v195
	v_lshlrev_b32_e32 v130, 16, v199
	v_rcp_f32_e32 v132, v131
	s_nop 0
	v_mul_f32_e32 v127, v127, v132
	v_rcp_f32_e32 v131, v130
	s_nop 0
	v_mul_f32_e32 v126, v126, v131
	v_pk_mul_f32 v[106:107], v[106:107], v[126:127]
	s_waitcnt vmcnt(0)
	v_and_b32_e32 v127, 0xffff0000, v168
	v_and_b32_e32 v131, 0xffff0000, v172
	v_lshlrev_b32_e32 v126, 16, v168
	v_lshlrev_b32_e32 v130, 16, v172
	v_rcp_f32_e32 v132, v131
	s_nop 0
	v_mul_f32_e32 v127, v127, v132
	v_rcp_f32_e32 v131, v130
	s_nop 0
	v_mul_f32_e32 v126, v126, v131
	v_pk_mul_f32 v[112:113], v[112:113], v[126:127]
	v_and_b32_e32 v127, 0xffff0000, v169
	v_and_b32_e32 v131, 0xffff0000, v173
	v_lshlrev_b32_e32 v126, 16, v169
	v_lshlrev_b32_e32 v130, 16, v173
	v_rcp_f32_e32 v132, v131
	s_nop 0
	v_mul_f32_e32 v127, v127, v132
	v_mov_b32_e32 v140, v248
	v_rcp_f32_e32 v131, v130
	s_nop 0
	v_mul_f32_e32 v126, v126, v131
	v_pk_mul_f32 v[114:115], v[114:115], v[126:127]
	v_ashrrev_i32_e32 v136, 8, v140
	v_cmp_eq_u32_e32 vcc, 1, v136
	s_and_saveexec_b64 s[62:63], vcc
	s_cbranch_execz .LBB0_564
	s_barrier
